# up-proj epilogue: conv-weight loads of the first column block issued before the halo-exchange barrier (round trip overlaps the barrier wait)
# speedup vs baseline: 1.0053x; 1.0030x over previous
;     DI void operator()(pg8::f32x4 (&acc)[2][2][4][2], const pg8::Unit& u, int wr, int wc, int fr, int fq) const {
;     ...
;         asm volatile("s_waitcnt lgkmcnt(0)\n\ts_barrier" ::: "memory");
; #pragma unroll
;         for (int n = 0; n < 2; ++n) {
;             v4f w0[2], w1[2], w2[2], cb[2];
; #pragma unroll
;             for (int bj = 0; bj < 2; ++bj) {
;                 const float* p = cwp + u.pn * 256 + bj * 128 + wc * 32 + 8 * fq + 4 * n;
;                 w0[bj] = *(const v4f*)p; w1[bj] = *(const v4f*)(p + NUP); w2[bj] = *(const v4f*)(p + 2 * NUP); cb[bj] = *(const v4f*)(p + 3 * NUP);
;             }
; #pragma unroll
;             for (int ai = 0; ai < 2; ++ai) {
;                 v4f hal[2];
;                 {
;                     const bool has = (wr == 1) || (ai == 1);
;                     const int as = (wr == 1) ? ai : 0, ws_ = (wr == 1) ? 0 : 1;
; #pragma unroll
;                     for (int bj = 0; bj < 2; ++bj) { v4f hv = H[(((as * 2 + ws_) * 4 + wc) * 4 + bj * 2 + n) * 8 + hl]; hal[bj] = has ? hv : (v4f){0.f, 0.f, 0.f, 0.f}; }
.LBB0_253:
	s_or_b64 exec, exec, s[26:27]
	v_lshl_add_u64 v[202:203], v[102:103], 2, v[186:187]
	v_add_co_u32_e32 v106, vcc, 0x5000, v202
	v_cndmask_b32_e64 v64, 0, 1, s[12:13]
	s_nop 0
	v_addc_co_u32_e32 v107, vcc, 0, v203, vcc
	v_add_co_u32_e32 v114, vcc, 0xb000, v202
	v_mov_b32_e32 v162, 0
	s_nop 0
	v_addc_co_u32_e32 v115, vcc, 0, v203, vcc
	v_add_co_u32_e32 v118, vcc, 0x10000, v202
	v_cmp_ne_u32_e64 s[42:43], 1, v64
	s_nop 0
	v_addc_co_u32_e32 v119, vcc, 0, v203, vcc
	global_load_dwordx4 v[122:125], v[202:203], off
	global_load_dwordx4 v[102:105], v[202:203], off offset:512
	global_load_dwordx4 v[126:129], v[106:107], off offset:2048
	s_nop 0
	global_load_dwordx4 v[106:109], v[106:107], off offset:2560
	s_nop 0
	global_load_dwordx4 v[130:133], v[114:115], off
	s_nop 0
	global_load_dwordx4 v[114:117], v[114:115], off offset:512
	s_nop 0
	global_load_dwordx4 v[134:137], v[118:119], off offset:2048
	s_nop 0
	global_load_dwordx4 v[118:121], v[118:119], off offset:2560
	s_waitcnt lgkmcnt(0)
	s_barrier
	s_andn2_b64 vcc, exec, s[12:13]
	v_add_u32_e32 v193, s54, v185
	v_mov_b32_e32 v166, 0
	v_mov_b32_e32 v167, 0
	v_mov_b32_e32 v168, 0
	v_mov_b32_e32 v169, 0
	s_cbranch_vccnz .LBB0_255
	ds_read_b128 v[166:169], v193
